# attention loops: per-segment setprio flips dropped, one static setprio 1 for waves 4-7 (lever 4), on top of the 16-byte-access version
# speedup vs baseline: 1.0057x; 1.0057x over previous
; #define LAS __attribute__((address_space(3)))
; template <int MODE, class Dec>
; __device__ __forceinline__ void attn_phase(const Frame& F, const bf16* Q, const bf16* K, const bf16* V, int nunits, const Dec dec, const bf16* O3, const float* L2, const float* L3) {
;     const int lane = F.lane, w = F.wave, g = lane >> 4, ql = lane & 15;
;     LAS unsigned char* lds = F.lds;
;     int u = F.vcu; if (u >= nunits) return;
;     AUnit cur, nxt; dec(u, cur); nxt = cur;
;     __syncthreads();
;     for (int i = F.tid; i < 2048; i += NWAVES * 64) { *(LAS v4u*)(lds + i * 16) = (v4u){0u, 0u, 0u, 0u}; *(LAS v4u*)(lds + 65536 + i * 16) = (v4u){0u, 0u, 0u, 0u}; }
;     __syncthreads();
;     attn_issue<false>(F, K, cur, 0); attn_issue<true>(F, V, cur, 65536);
.LBB0_421:
	s_cmpk_gt_i32 s93, 0xfff
	s_cbranch_scc1 .LBB0_472
	v_readfirstlane_b32 s0, v157
	s_lshr_b32 s0, s0, 8
	s_cmp_eq_u32 s0, 1
	s_cbranch_scc0 .Lprio2_done
	s_setprio 1
.Lprio2_done:
	s_add_u32 s12, s88, 0x2000000
	s_addc_u32 s13, s89, 0
	s_add_u32 s0, s88, 0x200000
	s_addc_u32 s1, s89, 0
	v_writelane_b32 v234, s0, 52
	s_nop 1
	v_writelane_b32 v234, s1, 53
	s_add_u32 s0, s88, 0x300000
	s_addc_u32 s1, s89, 0
	s_and_b32 s2, s93, 31
	v_writelane_b32 v234, s0, 54
	s_cmp_gt_u32 s2, 15
	s_nop 0
	v_writelane_b32 v234, s1, 55
	s_cbranch_scc0 .LBB0_425
	s_add_i32 s57, s2, -16
	s_mov_b64 s[62:63], s[12:13]
	s_mov_b32 s4, 0
	s_cbranch_execz .LBB0_426
	v_readlane_b32 s48, v234, 54
	s_movk_i32 s73, 0x800
	s_mov_b32 s82, 16
	v_readlane_b32 s49, v234, 55
	s_mov_b32 s75, 0
	s_branch .LBB0_427

; #define LAS __attribute__((address_space(3)))
; #define WG_BAR() do { asm volatile("s_waitcnt lgkmcnt(0)" ::: "memory"); __builtin_amdgcn_s_barrier(); asm volatile("" ::: "memory"); } while (0)
; template <int MODE, class Dec>
; __device__ __forceinline__ void attn_phase(const Frame& F, const bf16* Q, const bf16* K, const bf16* V, int nunits, const Dec dec, const bf16* O3, const float* L2, const float* L3) {
;     ...
;         WG_BAR();
;         const float sl = exp2f(-0.5f * (float)(h + 1)) * LOG2E * (float)d, cb = -sl * (float)(128 + ql - 4 * g);
;         f32x4 s[9];
;         __builtin_amdgcn_s_setprio(1);
; #pragma unroll
;         for (int tt = 0; tt < 9; ++tt) {
;             s[tt] = (f32x4){fmaf(sl, (float)(16 * tt), cb), fmaf(sl, (float)(16 * tt + 1), cb), fmaf(sl, (float)(16 * tt + 2), cb), fmaf(sl, (float)(16 * tt + 3), cb)};
; #pragma unroll
;             for (int ks = 0; ks < 4; ++ks) { const bf16x8 a = *(const LAS bf16x8*)(kb + ksw[ks] + tt * 4096); s[tt] = __builtin_amdgcn_mfma_f32_16x16x32_bf16(a, qf[ks], s[tt], 0, 0, 0); }
;         }
;         __builtin_amdgcn_s_setprio(0);
;         WG_BAR();
.LBB0_448:
	s_add_i32 s34, s56, 1
	v_cvt_f32_u32_e32 v16, s34
	s_mov_b32 s34, 0xc2fc0000
	s_waitcnt lgkmcnt(0)
	s_barrier
	v_mul_f32_e32 v17, -0.5, v16
	v_cmp_gt_f32_e32 vcc, s34, v17
	s_and_b64 s[34:35], vcc, exec
	s_cselect_b32 s34, 0xffffffc0, 0
	v_cndmask_b32_e32 v17, 0, v100, vcc
	v_fmac_f32_e32 v17, -0.5, v16
	v_exp_f32_e32 v16, v17
	v_cvt_f32_u32_e32 v17, s82
	v_ldexp_f32 v16, v16, s34
	v_mul_f32_e32 v16, 0x3fb8aa3b, v16
	v_mul_f32_e32 v80, v16, v17
	v_mul_f32_e64 v82, v81, -v80
	s_nop 0
	ds_read_b128 v[16:19], v96
	ds_read_b128 v[20:23], v96 offset:4096
	s_mov_b32 s34, 2.0
	s_mov_b32 s35, 0x40400000
	v_pk_fma_f32 v[26:27], v[80:81], s[34:35], v[82:83] op_sel_hi:[0,1,0]
	s_mov_b32 s34, 0x41900000
	v_fma_f32 v24, 0, v80, v82
	v_fma_f32 v25, v81, -v80, v80
	s_mov_b32 s35, 0x41980000
	ds_read_b128 v[48:51], v96 offset:32768
	ds_read_b128 v[28:31], v96 offset:8192
	s_waitcnt lgkmcnt(0)
	v_mfma_f32_16x16x32_bf16 v[16:19], v[16:19], v[12:15], v[24:27]
	s_nop 2
	v_fma_f32 v26, v80, s34, v82
	v_fma_f32 v27, v80, s35, v82
	s_mov_b32 s34, 0x41800000
	s_mov_b32 s35, 0x41880000
	v_pk_fma_f32 v[24:25], v[80:81], s[34:35], v[82:83] op_sel_hi:[0,1,0]
	s_mov_b32 s34, 0x42080000
	s_mov_b32 s35, 0x420c0000
	v_mfma_f32_16x16x32_bf16 v[20:23], v[20:23], v[12:15], v[24:27]
	s_nop 2
	ds_read_b128 v[24:27], v97
	ds_read_b128 v[32:35], v97 offset:4096
	s_waitcnt lgkmcnt(0)
	v_mfma_f32_16x16x32_bf16 v[16:19], v[24:27], v[8:11], v[16:19]
	ds_read_b128 v[24:27], v98
	ds_read_b128 v[104:107], v98 offset:32768
	s_waitcnt lgkmcnt(0)
	v_mfma_f32_16x16x32_bf16 v[16:19], v[24:27], v[4:7], v[16:19]
	ds_read_b128 v[24:27], v99
	ds_read_b128 v[36:39], v99 offset:4096
	s_waitcnt lgkmcnt(0)
	v_mfma_f32_16x16x32_bf16 v[44:47], v[24:27], v[0:3], v[16:19]
	v_mfma_f32_16x16x32_bf16 v[16:19], v[32:35], v[8:11], v[20:23]
	s_nop 2
	ds_read_b128 v[20:23], v98 offset:4096
	ds_read_b128 v[24:27], v98 offset:8192
	s_waitcnt lgkmcnt(0)
	v_mfma_f32_16x16x32_bf16 v[16:19], v[20:23], v[4:7], v[16:19]
	v_mfma_f32_16x16x32_bf16 v[36:39], v[36:39], v[0:3], v[16:19]
	s_nop 6
	v_fma_f32 v18, v80, s34, v82
	v_fma_f32 v19, v80, s35, v82
	s_mov_b32 s34, 0x42000000
	s_mov_b32 s35, 0x42040000
	v_pk_fma_f32 v[16:17], v[80:81], s[34:35], v[82:83] op_sel_hi:[0,1,0]
	s_mov_b32 s34, 0x42480000
	s_mov_b32 s35, 0x424c0000
	v_mfma_f32_16x16x32_bf16 v[16:19], v[28:31], v[12:15], v[16:19]
	ds_read_b128 v[20:23], v97 offset:8192
	ds_read_b128 v[28:31], v97 offset:12288
	s_waitcnt lgkmcnt(0)
	v_mfma_f32_16x16x32_bf16 v[16:19], v[20:23], v[8:11], v[16:19]
	ds_read_b128 v[20:23], v99 offset:8192
	v_mfma_f32_16x16x32_bf16 v[16:19], v[24:27], v[4:7], v[16:19]
	ds_read_b128 v[24:27], v96 offset:12288
	ds_read_b128 v[40:43], v99 offset:12288
	s_waitcnt lgkmcnt(0)
	v_mfma_f32_16x16x32_bf16 v[32:35], v[20:23], v[0:3], v[16:19]
	ds_read_b128 v[20:23], v96 offset:16384
	s_nop 2
	v_pk_fma_f32 v[18:19], v[80:81], s[34:35], v[82:83] op_sel_hi:[0,1,0]
	s_mov_b32 s34, 0x42400000
	s_mov_b32 s35, 0x42440000
	v_pk_fma_f32 v[16:17], v[80:81], s[34:35], v[82:83] op_sel_hi:[0,1,0]
	s_mov_b32 s34, 0x42840000
	s_mov_b32 s35, 0x42860000
	v_mfma_f32_16x16x32_bf16 v[16:19], v[24:27], v[12:15], v[16:19]
	ds_read_b128 v[24:27], v98 offset:12288
	ds_read_b128 v[108:111], v98 offset:16384
	v_mfma_f32_16x16x32_bf16 v[16:19], v[28:31], v[8:11], v[16:19]
	s_waitcnt lgkmcnt(0)
	v_mfma_f32_16x16x32_bf16 v[16:19], v[24:27], v[4:7], v[16:19]
	v_mfma_f32_16x16x32_bf16 v[28:31], v[40:43], v[0:3], v[16:19]
	s_nop 6
	v_fma_f32 v18, v80, s34, v82
	v_fma_f32 v19, v80, s35, v82
	s_mov_b32 s34, 0x42800000
	s_mov_b32 s35, 0x42820000
	v_pk_fma_f32 v[16:17], v[80:81], s[34:35], v[82:83] op_sel_hi:[0,1,0]
	s_mov_b32 s34, 0x42a40000
	s_mov_b32 s35, 0x42a60000
	v_mfma_f32_16x16x32_bf16 v[16:19], v[20:23], v[12:15], v[16:19]
	ds_read_b128 v[20:23], v97 offset:16384
	ds_read_b128 v[40:43], v97 offset:20480
	s_waitcnt lgkmcnt(0)
	v_mfma_f32_16x16x32_bf16 v[16:19], v[20:23], v[8:11], v[16:19]
	ds_read_b128 v[20:23], v99 offset:16384
	v_mfma_f32_16x16x32_bf16 v[16:19], v[108:111], v[4:7], v[16:19]
	ds_read_b128 v[108:111], v96 offset:20480
	ds_read_b128 v[112:115], v99 offset:20480
	ds_read_b128 v[116:119], v96 offset:24576
	s_waitcnt lgkmcnt(0)
	v_mfma_f32_16x16x32_bf16 v[24:27], v[20:23], v[0:3], v[16:19]
	s_nop 2
	v_fma_f32 v18, v80, s34, v82
	v_fma_f32 v19, v80, s35, v82
	s_mov_b32 s34, 0x42a00000
	s_mov_b32 s35, 0x42a20000
	v_pk_fma_f32 v[16:17], v[80:81], s[34:35], v[82:83] op_sel_hi:[0,1,0]
	s_mov_b32 s34, 0x42c40000
	s_mov_b32 s35, 0x42c60000
	v_mfma_f32_16x16x32_bf16 v[16:19], v[108:111], v[12:15], v[16:19]
	v_mfma_f32_16x16x32_bf16 v[16:19], v[40:43], v[8:11], v[16:19]
	ds_read_b128 v[20:23], v98 offset:20480
	ds_read_b128 v[40:43], v98 offset:24576
	s_waitcnt lgkmcnt(0)
	v_mfma_f32_16x16x32_bf16 v[16:19], v[20:23], v[4:7], v[16:19]
	v_mfma_f32_16x16x32_bf16 v[20:23], v[112:115], v[0:3], v[16:19]
	ds_read_b128 v[108:111], v97 offset:24576
	ds_read_b128 v[112:115], v97 offset:28672
	s_nop 4
	v_pk_fma_f32 v[18:19], v[80:81], s[34:35], v[82:83] op_sel_hi:[0,1,0]
	v_pk_fma_f32 v[16:17], v[80:81], s[54:55], v[82:83] op_sel_hi:[0,1,0]
	s_nop 1
	v_mfma_f32_16x16x32_bf16 v[16:19], v[116:119], v[12:15], v[16:19]
	s_waitcnt lgkmcnt(0)
	v_mfma_f32_16x16x32_bf16 v[16:19], v[108:111], v[8:11], v[16:19]
	ds_read_b128 v[108:111], v99 offset:24576
	v_mfma_f32_16x16x32_bf16 v[16:19], v[40:43], v[4:7], v[16:19]
	ds_read_b128 v[40:43], v96 offset:28672
	ds_read_b128 v[116:119], v99 offset:28672
	ds_read_b128 v[120:123], v97 offset:32768
	s_waitcnt lgkmcnt(0)
	v_mfma_f32_16x16x32_bf16 v[16:19], v[108:111], v[0:3], v[16:19]
	v_fma_f32 v110, v80, s38, v82
	v_fma_f32 v111, v80, s39, v82
	v_pk_fma_f32 v[108:109], v[80:81], s[40:41], v[82:83] op_sel_hi:[0,1,0]
	s_nop 1
	v_mfma_f32_16x16x32_bf16 v[40:43], v[40:43], v[12:15], v[108:111]
	v_mfma_f32_16x16x32_bf16 v[40:43], v[112:115], v[8:11], v[40:43]
	s_nop 1
	ds_read_b128 v[108:111], v98 offset:28672
	ds_read_b128 v[112:115], v99 offset:32768
	s_waitcnt lgkmcnt(0)
	v_mfma_f32_16x16x32_bf16 v[40:43], v[108:111], v[4:7], v[40:43]
	v_fma_f32 v110, v80, s42, v82
	v_fma_f32 v111, v80, s43, v82
	v_pk_fma_f32 v[108:109], v[80:81], s[50:51], v[82:83] op_sel_hi:[0,1,0]
	v_mfma_f32_16x16x32_bf16 v[40:43], v[116:119], v[0:3], v[40:43]
	s_nop 0
	v_mfma_f32_16x16x32_bf16 v[48:51], v[48:51], v[12:15], v[108:111]
	v_mfma_f32_16x16x32_bf16 v[48:51], v[120:123], v[8:11], v[48:51]
	v_mfma_f32_16x16x32_bf16 v[48:51], v[104:107], v[4:7], v[48:51]
	v_mfma_f32_16x16x32_bf16 v[48:51], v[112:115], v[0:3], v[48:51]
	s_nop 0
	s_waitcnt lgkmcnt(0)
	s_barrier
	v_cndmask_b32_e64 v79, 0, 1, s[66:67]
	v_cmp_ne_u32_e64 s[34:35], 1, v79
	s_andn2_b64 vcc, exec, s[66:67]
	s_cbranch_vccnz .LBB0_455
	s_lshl_b32 s96, s83, 11
	s_cmp_gt_i32 s81, 0
	s_mov_b64 s[66:67], -1
	s_cbranch_scc1 .LBB0_451
	s_add_i32 s95, s96, s79
	s_lshl_b32 s60, s94, 7
	s_mov_b64 s[66:67], 0

; template <int MODE, class Dec>
; __device__ __forceinline__ void attn_phase(const Frame& F, const bf16* Q, const bf16* K, const bf16* V, int nunits, const Dec dec, const bf16* O3, const float* L2, const float* L3) {
;     ...
;         bf16* op = cur.Og + qrow * (size_t)cur.ldo + h * 128 + 4 * g;
;         if (MODE == 1) { const bf16* o3p = O3 + qrow * 2048 + h * 128 + 4 * g;
; #pragma unroll
;             for (int dt = 0; dt < 8; ++dt) { a2[dt] = *(const v2u*)(op + 16 * dt); a3[dt] = *(const v2u*)(o3p + 16 * dt); }
;             l2v = L2[qrow * 16 + h]; l3v = L3[qrow * 16 + h]; }
;         if (has_next) { attn_issue<false>(F, K, nxt, 0);
;             q_load4(Q + (size_t)(nxt.b * SEQ + (nxt.n * 128 + qi) * nxt.d + nxt.r) * 2048 + nxt.h * 128 + 8 * g, qn); }
; #pragma unroll
;         for (int e = 0; e < 4; ++e) { if (4 * g + e < ql) s[0][e] = NEG; if (4 * g + e > ql) s[8][e] = NEG; }
;         if (n == 0) {
; #pragma unroll
;             for (int tt = 0; tt < 8; ++tt) { const bool dead = (w + tt < 8);
; #pragma unroll
;                 for (int e = 0; e < 4; ++e) s[tt][e] = dead ? NEG : s[tt][e]; } }
;         float mx = NEG;
; #pragma unroll
;         for (int tt = 0; tt < 9; ++tt) mx = fmaxf(fmaxf(mx, fmaxf(s[tt][0], s[tt][1])), fmaxf(s[tt][2], s[tt][3]));
;         mx = fmaxf(mx, __shfl_xor(mx, 16)); mx = fmaxf(mx, __shfl_xor(mx, 32));
;         float l = 0.f;
; #pragma unroll
;         for (int tt = 0; tt < 9; ++tt)
; #pragma unroll
;             for (int e = 0; e < 4; ++e) { const float p = __builtin_amdgcn_exp2f(s[tt][e] - mx); s[tt][e] = p; l += p; }
;         l += __shfl_xor(l, 16); l += __shfl_xor(l, 32);
;         bf16x8 pf[5];
; #pragma unroll
;         for (int pp = 0; pp < 5; ++pp) { const f32x4 px = s[2 * pp], py = (pp < 4) ? s[2 * pp + 1] : (f32x4){0.f, 0.f, 0.f, 0.f};
;             v4u u4; u4.x = pg8::cvt_pk_bf16(px[0], px[1]); u4.y = pg8::cvt_pk_bf16(px[2], px[3]); u4.z = pg8::cvt_pk_bf16(py[0], py[1]); u4.w = pg8::cvt_pk_bf16(py[2], py[3]);
;             pf[pp] = __builtin_bit_cast(bf16x8, u4); }
;         if (has_next) { if (nxt.n > 0) asm volatile("s_waitcnt vmcnt(12)" ::: "memory"); else asm volatile("s_waitcnt vmcnt(8)" ::: "memory"); }
;         else asm volatile("s_waitcnt vmcnt(0)" ::: "memory");
;         WG_BAR();
;         f32x4 o[8];
;         s16x4 vfa[10], vfb[10];
.LBB0_464:
	s_waitcnt lgkmcnt(0)
	v_add_f32_e32 v49, v36, v37
	s_lshl_b32 s60, s76, 11
	v_lshl_add_u32 v36, s75, 7, v87
	v_mul_lo_u32 v36, v36, s82
	s_add_i32 s60, s60, s57
	v_add_u32_e32 v44, s60, v36
	v_mad_u64_u32 v[36:37], s[64:65], v44, s73, 0
	v_ashrrev_i32_e32 v45, 31, v44
	v_mov_b32_e32 v38, v37
	v_mad_u64_u32 v[38:39], s[64:65], v45, s73, v[38:39]
	v_mov_b32_e32 v37, v38
	v_lshl_add_u64 v[36:37], v[36:37], 1, s[62:63]
	s_lshl_b32 s60, s56, 8
	v_lshl_add_u64 v[36:37], v[36:37], 0, s[60:61]
	s_waitcnt lgkmcnt(0)
	s_barrier
	v_lshl_add_u64 v[46:47], v[36:37], 0, v[62:63]
	ds_read_b64_tr_b16 v[112:113], v88
	ds_read_b64_tr_b16 v[114:115], v88 offset:4096
	ds_read_b64_tr_b16 v[108:109], v88 offset:8192
	ds_read_b64_tr_b16 v[110:111], v88 offset:12288
	ds_read_b64_tr_b16 v[104:105], v88 offset:16384
	ds_read_b64_tr_b16 v[106:107], v88 offset:20480
	ds_read_b64_tr_b16 v[40:41], v88 offset:24576
	ds_read_b64_tr_b16 v[42:43], v88 offset:28672
	ds_read_b64_tr_b16 v[36:37], v88 offset:32768
	ds_read_b64_tr_b16 v[38:39], v88 offset:32768
	ds_read_b64_tr_b16 v[132:133], v89
	ds_read_b64_tr_b16 v[134:135], v89 offset:4096
	ds_read_b64_tr_b16 v[128:129], v89 offset:8192
	ds_read_b64_tr_b16 v[130:131], v89 offset:12288
	ds_read_b64_tr_b16 v[124:125], v89 offset:16384
	ds_read_b64_tr_b16 v[126:127], v89 offset:20480
	ds_read_b64_tr_b16 v[120:121], v89 offset:24576
	ds_read_b64_tr_b16 v[122:123], v89 offset:28672
	ds_read_b64_tr_b16 v[116:117], v89 offset:32768
	ds_read_b64_tr_b16 v[118:119], v89 offset:32768
	s_nop 0
	s_waitcnt lgkmcnt(10)
	s_nop 0
	v_mfma_f32_16x16x32_bf16 v[112:115], v[112:115], v[32:35], 0
	v_mfma_f32_16x16x32_bf16 v[108:111], v[108:111], v[28:31], v[112:115]
	v_mfma_f32_16x16x32_bf16 v[104:107], v[104:107], v[24:27], v[108:111]
	v_mfma_f32_16x16x32_bf16 v[40:43], v[40:43], v[20:23], v[104:107]
	v_mfma_f32_16x16x32_bf16 v[36:39], v[36:39], v[16:19], v[40:43]
	s_nop 0
	ds_read_b64_tr_b16 v[140:141], v90
	ds_read_b64_tr_b16 v[142:143], v90 offset:4096
	ds_read_b64_tr_b16 v[136:137], v90 offset:8192
	ds_read_b64_tr_b16 v[138:139], v90 offset:12288
	ds_read_b64_tr_b16 v[112:113], v90 offset:16384
	ds_read_b64_tr_b16 v[114:115], v90 offset:20480
	ds_read_b64_tr_b16 v[108:109], v90 offset:24576
	ds_read_b64_tr_b16 v[110:111], v90 offset:28672
	ds_read_b64_tr_b16 v[104:105], v90 offset:32768
	ds_read_b64_tr_b16 v[106:107], v90 offset:32768
	s_waitcnt lgkmcnt(10)
	s_nop 0
	v_mfma_f32_16x16x32_bf16 v[40:43], v[132:135], v[32:35], 0
	v_mfma_f32_16x16x32_bf16 v[40:43], v[128:131], v[28:31], v[40:43]
	v_mfma_f32_16x16x32_bf16 v[40:43], v[124:127], v[24:27], v[40:43]
	v_mfma_f32_16x16x32_bf16 v[40:43], v[120:123], v[20:23], v[40:43]
	v_mfma_f32_16x16x32_bf16 v[40:43], v[116:119], v[16:19], v[40:43]
	s_nop 0
	ds_read_b64_tr_b16 v[132:133], v91
	ds_read_b64_tr_b16 v[134:135], v91 offset:4096
	ds_read_b64_tr_b16 v[128:129], v91 offset:8192
	ds_read_b64_tr_b16 v[130:131], v91 offset:12288
	ds_read_b64_tr_b16 v[124:125], v91 offset:16384
	ds_read_b64_tr_b16 v[126:127], v91 offset:20480
	ds_read_b64_tr_b16 v[120:121], v91 offset:24576
	ds_read_b64_tr_b16 v[122:123], v91 offset:28672
	ds_read_b64_tr_b16 v[116:117], v91 offset:32768
	ds_read_b64_tr_b16 v[118:119], v91 offset:32768
	s_waitcnt lgkmcnt(10)
	s_nop 0
	v_mfma_f32_16x16x32_bf16 v[140:143], v[140:143], v[32:35], 0
	v_mfma_f32_16x16x32_bf16 v[136:139], v[136:139], v[28:31], v[140:143]
	v_mfma_f32_16x16x32_bf16 v[112:115], v[112:115], v[24:27], v[136:139]
	v_mfma_f32_16x16x32_bf16 v[108:111], v[108:111], v[20:23], v[112:115]
	v_mfma_f32_16x16x32_bf16 v[104:107], v[104:107], v[16:19], v[108:111]
	s_nop 0
	ds_read_b64_tr_b16 v[144:145], v92
	ds_read_b64_tr_b16 v[146:147], v92 offset:4096
	ds_read_b64_tr_b16 v[140:141], v92 offset:8192
	ds_read_b64_tr_b16 v[142:143], v92 offset:12288
	ds_read_b64_tr_b16 v[136:137], v92 offset:16384
	ds_read_b64_tr_b16 v[138:139], v92 offset:20480
	ds_read_b64_tr_b16 v[112:113], v92 offset:24576
	ds_read_b64_tr_b16 v[114:115], v92 offset:28672
	ds_read_b64_tr_b16 v[108:109], v92 offset:32768
	ds_read_b64_tr_b16 v[110:111], v92 offset:32768
	s_waitcnt lgkmcnt(10)
	s_nop 0
	v_mfma_f32_16x16x32_bf16 v[132:135], v[132:135], v[32:35], 0
	v_mfma_f32_16x16x32_bf16 v[128:131], v[128:131], v[28:31], v[132:135]
	v_mfma_f32_16x16x32_bf16 v[124:127], v[124:127], v[24:27], v[128:131]
	v_mfma_f32_16x16x32_bf16 v[120:123], v[120:123], v[20:23], v[124:127]
	v_mfma_f32_16x16x32_bf16 v[116:119], v[116:119], v[16:19], v[120:123]
	s_nop 0
	ds_read_b64_tr_b16 v[148:149], v93
	ds_read_b64_tr_b16 v[150:151], v93 offset:4096
	ds_read_b64_tr_b16 v[132:133], v93 offset:8192
	ds_read_b64_tr_b16 v[134:135], v93 offset:12288
	ds_read_b64_tr_b16 v[128:129], v93 offset:16384
	ds_read_b64_tr_b16 v[130:131], v93 offset:20480
	ds_read_b64_tr_b16 v[124:125], v93 offset:24576
	ds_read_b64_tr_b16 v[126:127], v93 offset:28672
	ds_read_b64_tr_b16 v[120:121], v93 offset:32768
	ds_read_b64_tr_b16 v[122:123], v93 offset:32768
	s_waitcnt lgkmcnt(10)
; __device__ __forceinline__ unsigned cvt_pk_bf16(float lo, float hi) { unsigned r; asm volatile("v_cvt_pk_bf16_f32 %0, %1, %2" : "=v"(r) : "v"(lo), "v"(hi)); return r; }
; #define WG_BAR() do { asm volatile("s_waitcnt lgkmcnt(0)" ::: "memory"); __builtin_amdgcn_s_barrier(); asm volatile("" ::: "memory"); } while (0)
; template <int MODE, class Dec>
; __device__ __forceinline__ void attn_phase(const Frame& F, const bf16* Q, const bf16* K, const bf16* V, int nunits, const Dec dec, const bf16* O3, const float* L2, const float* L3) {
;     ...
;         for (int dt = 0; dt < 8; dt += 2) {
;             tr_issue10((unsigned)(size_t)(vb + (((2 * (dt + 1) + (p4 >> 1)) ^ frl) << 4)), vfb);
;             tr_wait10<10>(vfa);
;             __builtin_amdgcn_s_setprio(1);
;             o[dt] = (f32x4){0.f, 0.f, 0.f, 0.f};
; #pragma unroll
;             for (int pp = 0; pp < 5; ++pp) { const bf16x8 a = __builtin_shufflevector(vfa[2 * pp], vfa[2 * pp + 1], 0, 1, 2, 3, 4, 5, 6, 7);
;                 o[dt] = __builtin_amdgcn_mfma_f32_16x16x32_bf16(a, pf[pp], o[dt], 0, 0, 0); }
;             __builtin_amdgcn_s_setprio(0);
;             if (dt + 2 < 8) { tr_issue10((unsigned)(size_t)(vb + (((2 * (dt + 2) + (p4 >> 1)) ^ frl) << 4)), vfa); tr_wait10<10>(vfb); } else tr_wait10<0>(vfb);
;             __builtin_amdgcn_s_setprio(1);
;             o[dt + 1] = (f32x4){0.f, 0.f, 0.f, 0.f};
; #pragma unroll
;             for (int pp = 0; pp < 5; ++pp) { const bf16x8 a = __builtin_shufflevector(vfb[2 * pp], vfb[2 * pp + 1], 0, 1, 2, 3, 4, 5, 6, 7);
;                 o[dt + 1] = __builtin_amdgcn_mfma_f32_16x16x32_bf16(a, pf[pp], o[dt + 1], 0, 0, 0); }
;             __builtin_amdgcn_s_setprio(0);
;         }
;         WG_BAR();
;         asm volatile("s_waitcnt vmcnt(0)" ::: "memory");
;         const float linv = 1.0f / l, lse = mx + __builtin_amdgcn_logf(l);
;         if (MODE == 0) {
; #pragma unroll
;             for (int dt = 0; dt < 8; ++dt) { v2u wv; wv.x = pg8::cvt_pk_bf16(o[dt][0] * linv, o[dt][1] * linv); wv.y = pg8::cvt_pk_bf16(o[dt][2] * linv, o[dt][3] * linv); *(v2u*)(op + 16 * dt) = wv; }
;             if (g == 0) cur.Lg[qrow * 16 + h] = lse;
	s_nop 0
	v_mfma_f32_16x16x32_bf16 v[144:147], v[144:147], v[32:35], 0
	v_mfma_f32_16x16x32_bf16 v[140:143], v[140:143], v[28:31], v[144:147]
	v_mfma_f32_16x16x32_bf16 v[136:139], v[136:139], v[24:27], v[140:143]
	v_mfma_f32_16x16x32_bf16 v[112:115], v[112:115], v[20:23], v[136:139]
	v_mfma_f32_16x16x32_bf16 v[108:111], v[108:111], v[16:19], v[112:115]
	s_nop 0
	ds_read_b64_tr_b16 v[152:153], v94
	ds_read_b64_tr_b16 v[154:155], v94 offset:4096
	ds_read_b64_tr_b16 v[144:145], v94 offset:8192
	ds_read_b64_tr_b16 v[146:147], v94 offset:12288
	ds_read_b64_tr_b16 v[140:141], v94 offset:16384
	ds_read_b64_tr_b16 v[142:143], v94 offset:20480
	ds_read_b64_tr_b16 v[136:137], v94 offset:24576
	ds_read_b64_tr_b16 v[138:139], v94 offset:28672
	ds_read_b64_tr_b16 v[112:113], v94 offset:32768
	ds_read_b64_tr_b16 v[114:115], v94 offset:32768
	s_waitcnt lgkmcnt(10)
	s_nop 0
	v_mfma_f32_16x16x32_bf16 v[148:151], v[148:151], v[32:35], 0
	v_mfma_f32_16x16x32_bf16 v[132:135], v[132:135], v[28:31], v[148:151]
	v_mfma_f32_16x16x32_bf16 v[128:131], v[128:131], v[24:27], v[132:135]
	v_mfma_f32_16x16x32_bf16 v[124:127], v[124:127], v[20:23], v[128:131]
	v_mfma_f32_16x16x32_bf16 v[120:123], v[120:123], v[16:19], v[124:127]
	s_nop 0
	ds_read_b64_tr_b16 v[158:159], v95
	ds_read_b64_tr_b16 v[160:161], v95 offset:4096
	ds_read_b64_tr_b16 v[148:149], v95 offset:8192
	ds_read_b64_tr_b16 v[150:151], v95 offset:12288
	ds_read_b64_tr_b16 v[132:133], v95 offset:16384
	ds_read_b64_tr_b16 v[134:135], v95 offset:20480
	ds_read_b64_tr_b16 v[128:129], v95 offset:24576
	ds_read_b64_tr_b16 v[130:131], v95 offset:28672
	ds_read_b64_tr_b16 v[124:125], v95 offset:32768
	ds_read_b64_tr_b16 v[126:127], v95 offset:32768
	s_waitcnt lgkmcnt(10)
	s_nop 0
	v_mfma_f32_16x16x32_bf16 v[152:155], v[152:155], v[32:35], 0
	v_mfma_f32_16x16x32_bf16 v[144:147], v[144:147], v[28:31], v[152:155]
	v_mfma_f32_16x16x32_bf16 v[140:143], v[140:143], v[24:27], v[144:147]
	v_mfma_f32_16x16x32_bf16 v[136:139], v[136:139], v[20:23], v[140:143]
	v_mfma_f32_16x16x32_bf16 v[112:115], v[112:115], v[16:19], v[136:139]
	s_nop 0
	s_waitcnt lgkmcnt(0)
	s_nop 0
	v_mfma_f32_16x16x32_bf16 v[32:35], v[158:161], v[32:35], 0
	v_mfma_f32_16x16x32_bf16 v[28:31], v[148:151], v[28:31], v[32:35]
	v_mfma_f32_16x16x32_bf16 v[24:27], v[132:135], v[24:27], v[28:31]
	v_mfma_f32_16x16x32_bf16 v[20:23], v[128:131], v[20:23], v[24:27]
	v_mfma_f32_16x16x32_bf16 v[16:19], v[124:127], v[16:19], v[20:23]
	s_nop 0
	s_nop 5
	v_div_scale_f32 v20, s[62:63], v49, v49, 1.0
	v_rcp_f32_e32 v21, v20
	s_waitcnt lgkmcnt(0)
	s_barrier
	v_fma_f32 v22, -v20, v21, 1.0
	v_fmac_f32_e32 v21, v22, v21
	v_div_scale_f32 v22, vcc, 1.0, v49, 1.0
	v_mul_f32_e32 v23, v22, v21
	v_fma_f32 v24, -v20, v23, v22
	v_fmac_f32_e32 v23, v24, v21
	v_fma_f32 v20, -v20, v23, v22
	v_div_fmas_f32 v20, v20, v21, v23
	v_div_fixup_f32 v22, v20, v49, 1.0
	v_mul_f32_e32 v20, v22, v36
	v_mul_f32_e32 v21, v22, v37
	s_waitcnt vmcnt(0)
	v_cvt_pk_bf16_f32 v20, v20, v21
	v_mul_f32_e32 v21, v22, v38
	v_mul_f32_e32 v23, v22, v39
	v_cvt_pk_bf16_f32 v21, v21, v23
	v_bfe_u32 v242, v156, 4, 1
	v_mul_u32_u24_e32 v242, 24, v242
	v_mov_b32_e32 v243, 0
	v_lshl_add_u64 v[240:241], v[46:47], 0, v[242:243]
	v_mov_b32_e32 v236, v20
	v_mov_b32_e32 v237, v21
	v_mul_f32_e32 v20, v22, v40
	v_mul_f32_e32 v21, v22, v41
	v_cvt_pk_bf16_f32 v20, v20, v21
	v_mul_f32_e32 v21, v22, v42
	v_mul_f32_e32 v23, v22, v43
	v_cvt_pk_bf16_f32 v21, v21, v23
	v_mov_b32_e32 v238, v20
	v_mov_b32_e32 v239, v21
	s_nop 1
	v_permlane16_swap_b32 v236, v238
	v_permlane16_swap_b32 v237, v239
	global_store_dwordx4 v[240:241], v[236:239], off
	v_mul_f32_e32 v20, v22, v104
	v_mul_f32_e32 v21, v22, v105
	v_cvt_pk_bf16_f32 v20, v20, v21
	v_mul_f32_e32 v21, v22, v106
	v_mul_f32_e32 v23, v22, v107
	v_cvt_pk_bf16_f32 v21, v21, v23
	v_mov_b32_e32 v236, v20
	v_mov_b32_e32 v237, v21
	v_mul_f32_e32 v20, v22, v116
	v_mul_f32_e32 v21, v22, v117
	v_cvt_pk_bf16_f32 v20, v20, v21
	v_mul_f32_e32 v21, v22, v118
	v_mul_f32_e32 v23, v22, v119
	v_cvt_pk_bf16_f32 v21, v21, v23
	v_mov_b32_e32 v238, v20
	v_mov_b32_e32 v239, v21
	s_nop 1
	v_permlane16_swap_b32 v236, v238
	v_permlane16_swap_b32 v237, v239
	global_store_dwordx4 v[240:241], v[236:239], off offset:64
	v_mul_f32_e32 v20, v22, v108
	v_mul_f32_e32 v21, v22, v109
	v_cvt_pk_bf16_f32 v20, v20, v21
	v_mul_f32_e32 v21, v22, v110
	v_mul_f32_e32 v23, v22, v111
	v_cvt_pk_bf16_f32 v21, v21, v23
	v_mov_b32_e32 v236, v20
	v_mov_b32_e32 v237, v21
	v_mul_f32_e32 v20, v22, v120
	v_mul_f32_e32 v21, v22, v121
	v_cvt_pk_bf16_f32 v20, v20, v21
	v_mul_f32_e32 v21, v22, v122
	v_mul_f32_e32 v23, v22, v123
	v_cvt_pk_bf16_f32 v21, v21, v23
	v_mov_b32_e32 v238, v20
	v_mov_b32_e32 v239, v21
	s_nop 1
	v_permlane16_swap_b32 v236, v238
	v_permlane16_swap_b32 v237, v239
	global_store_dwordx4 v[240:241], v[236:239], off offset:128
	v_mul_f32_e32 v20, v22, v112
	v_mul_f32_e32 v21, v22, v113
	v_cvt_pk_bf16_f32 v20, v20, v21
	v_mul_f32_e32 v21, v22, v114
	v_mul_f32_e32 v16, v22, v16
	v_mul_f32_e32 v17, v22, v17
	v_mul_f32_e32 v23, v22, v115
	v_cvt_pk_bf16_f32 v21, v21, v23
	v_mov_b32_e32 v236, v20
	v_mov_b32_e32 v237, v21
	v_cvt_pk_bf16_f32 v16, v16, v17
	v_mul_f32_e32 v17, v22, v18
	v_mul_f32_e32 v18, v22, v19
	v_cvt_pk_bf16_f32 v17, v17, v18
	v_mov_b32_e32 v238, v16
	v_mov_b32_e32 v239, v17
	s_nop 1
	v_permlane16_swap_b32 v236, v238
	v_permlane16_swap_b32 v237, v239
	global_store_dwordx4 v[240:241], v[236:239], off offset:192
	s_and_saveexec_b64 s[62:63], s[0:1]
	s_cbranch_execz .LBB0_466
	v_log_f32_e32 v18, v49
	v_lshlrev_b64 v[16:17], 6, v[44:45]
	v_lshl_add_u64 v[16:17], s[48:49], 0, v[16:17]
	s_mov_b32 s57, s61
	v_lshl_add_u64 v[16:17], s[56:57], 2, v[16:17]
	v_add_f32_e32 v18, v48, v18
	global_store_dword v[16:17], v18, off

; template <int MODE, class Dec>
; __device__ __forceinline__ void attn_phase(const Frame& F, const bf16* Q, const bf16* K, const bf16* V, int nunits, const Dec dec, const bf16* O3, const float* L2, const float* L3) {
;     ...
;     asm volatile("s_waitcnt vmcnt(0)" ::: "memory");
;     __syncthreads();
.LBB0_471:
	s_setprio 0
	s_waitcnt vmcnt(0)
	v_readlane_b32 s80, v234, 45
	v_readlane_b32 s74, v234, 41
	v_readlane_b32 s78, v234, 43
	v_readlane_b32 s81, v234, 46
	v_readlane_b32 s93, v234, 47
	v_readlane_b32 s83, v234, 49
	v_readlane_b32 s92, v234, 48
	s_waitcnt vmcnt(0) lgkmcnt(0)
	s_barrier
	v_readlane_b32 s75, v234, 42
	v_readlane_b32 s79, v234, 44

; #define LAS __attribute__((address_space(3)))
; template <int MODE, class Dec>
; __device__ __forceinline__ void attn_phase(const Frame& F, const bf16* Q, const bf16* K, const bf16* V, int nunits, const Dec dec, const bf16* O3, const float* L2, const float* L3) {
;     ...
;     int u = F.vcu; if (u >= nunits) return;
;     AUnit cur, nxt; dec(u, cur); nxt = cur;
;     __syncthreads();
;     for (int i = F.tid; i < 2048; i += NWAVES * 64) { *(LAS v4u*)(lds + i * 16) = (v4u){0u, 0u, 0u, 0u}; *(LAS v4u*)(lds + 65536 + i * 16) = (v4u){0u, 0u, 0u, 0u}; }
;     __syncthreads();
.LBB0_522:
	s_cmp_lt_i32 s90, 4
	s_cselect_b64 s[2:3], -1, 0
	s_and_b64 s[2:3], s[2:3], s[0:1]
	s_andn2_b64 vcc, exec, s[2:3]
	s_cbranch_vccnz .LBB0_559
	s_cmpk_gt_i32 s93, 0x7ff
	s_cbranch_scc1 .LBB0_559
	v_readfirstlane_b32 s4, v157
	s_lshr_b32 s4, s4, 8
	s_cmp_eq_u32 s4, 1
	s_cbranch_scc0 .Lprio3_done
	s_setprio 1
.Lprio3_done:
	s_mov_b32 s4, 0
	s_mov_b32 s5, s4
	v_writelane_b32 v234, s2, 57
	s_mov_b32 s6, s4
	s_mov_b32 s7, s4
	v_mov_b64_e32 v[2:3], s[4:5]
	v_writelane_b32 v234, s3, 58
	v_add_u32_e32 v0, 0xfffffe00, v157
	v_lshl_add_u32 v1, v157, 4, 0
	s_mov_b64 s[0:1], 0
	v_mov_b64_e32 v[4:5], s[6:7]
	s_movk_i32 s2, 0x5ff
	s_waitcnt vmcnt(0)
	s_barrier

; #define LAS __attribute__((address_space(3)))
; #define WG_BAR() do { asm volatile("s_waitcnt lgkmcnt(0)" ::: "memory"); __builtin_amdgcn_s_barrier(); asm volatile("" ::: "memory"); } while (0)
; template <int MODE, class Dec>
; __device__ __forceinline__ void attn_phase(const Frame& F, const bf16* Q, const bf16* K, const bf16* V, int nunits, const Dec dec, const bf16* O3, const float* L2, const float* L3) {
;     ...
;         const int un = u + F.G; const bool has_next = un < nunits; if (has_next) dec(un, nxt);
;         const int n = cur.n, h = cur.h, d = cur.d;
;         const int qi = 16 * w + ql;
;         const size_t qrow = (size_t)(cur.b * SEQ + (n * 128 + qi) * d + cur.r);
;         WG_BAR();
;         const float sl = exp2f(-0.5f * (float)(h + 1)) * LOG2E * (float)d, cb = -sl * (float)(128 + ql - 4 * g);
;         f32x4 s[9];
;         __builtin_amdgcn_s_setprio(1);
; #pragma unroll
;         for (int tt = 0; tt < 9; ++tt) {
;             s[tt] = (f32x4){fmaf(sl, (float)(16 * tt), cb), fmaf(sl, (float)(16 * tt + 1), cb), fmaf(sl, (float)(16 * tt + 2), cb), fmaf(sl, (float)(16 * tt + 3), cb)};
; #pragma unroll
;             for (int ks = 0; ks < 4; ++ks) { const bf16x8 a = *(const LAS bf16x8*)(kb + ksw[ks] + tt * 4096); s[tt] = __builtin_amdgcn_mfma_f32_16x16x32_bf16(a, qf[ks], s[tt], 0, 0, 0); }
;         }
.LBB0_539:
	s_cmpk_lt_i32 s62, 0x800
	s_cselect_b64 s[50:51], -1, 0
	s_cmpk_gt_i32 s62, 0x7ff
	s_mov_b32 s92, s34
	s_cselect_b64 s[2:3], -1, 0
	s_lshl_b32 s48, s48, 11
	s_lshl_b32 s66, s65, 7
	s_add_i32 s48, s48, s66
	s_add_i32 s66, s92, 1
	v_cvt_f32_u32_e32 v16, s66
	v_add_u32_e32 v52, s48, v130
	s_mov_b32 s48, 0xc2fc0000
	s_bfe_u32 s34, s62, 0x40004
	v_mul_f32_e32 v17, -0.5, v16
	v_cmp_gt_f32_e32 vcc, s48, v17
	s_ashr_i32 s64, s62, 8
	s_and_b64 s[66:67], vcc, exec
	v_cndmask_b32_e32 v17, 0, v144, vcc
	v_fmac_f32_e32 v17, -0.5, v16
	v_exp_f32_e32 v16, v17
	s_waitcnt lgkmcnt(0)
	s_barrier
	s_cselect_b32 s48, 0xffffffc0, 0
	v_ldexp_f32 v16, v16, s48
	v_mul_f32_e32 v54, 0x3fb8aa3b, v16
	v_mul_f32_e64 v56, v131, -v54
	s_nop 0
	ds_read_b128 v[20:23], v140
	ds_read_b128 v[48:51], v140 offset:28672
	s_mov_b32 s66, 2.0
	s_mov_b32 s67, 0x40400000
	v_fma_f32 v16, 0, v54, v56
	v_fma_f32 v17, v131, -v54, v54
	v_pk_fma_f32 v[18:19], v[54:55], s[66:67], v[56:57] op_sel_hi:[0,1,0]
	s_mov_b32 s66, 0x41900000
	s_mov_b32 s67, 0x41980000
	s_waitcnt lgkmcnt(0)
	v_mfma_f32_16x16x32_bf16 v[16:19], v[20:23], v[0:3], v[16:19]
	ds_read_b128 v[20:23], v141
	v_ashrrev_i32_e32 v53, 31, v52
	s_waitcnt lgkmcnt(0)
	v_mfma_f32_16x16x32_bf16 v[16:19], v[20:23], v[4:7], v[16:19]
	ds_read_b128 v[20:23], v142
	s_waitcnt lgkmcnt(0)
	v_mfma_f32_16x16x32_bf16 v[16:19], v[20:23], v[8:11], v[16:19]
	ds_read_b128 v[20:23], v143
	s_waitcnt lgkmcnt(0)
	v_mfma_f32_16x16x32_bf16 v[44:47], v[20:23], v[12:15], v[16:19]
	ds_read_b128 v[20:23], v140 offset:4096
	s_nop 3
	v_pk_fma_f32 v[18:19], v[54:55], s[66:67], v[56:57] op_sel_hi:[0,1,0]
	s_mov_b32 s66, 0x41800000
	s_mov_b32 s67, 0x41880000
	v_pk_fma_f32 v[16:17], v[54:55], s[66:67], v[56:57] op_sel_hi:[0,1,0]
	s_mov_b32 s66, 0x42080000
	s_mov_b32 s67, 0x420c0000
	s_waitcnt lgkmcnt(0)
	v_mfma_f32_16x16x32_bf16 v[16:19], v[20:23], v[0:3], v[16:19]
	ds_read_b128 v[20:23], v141 offset:4096
	s_waitcnt lgkmcnt(0)
	v_mfma_f32_16x16x32_bf16 v[16:19], v[20:23], v[4:7], v[16:19]
	ds_read_b128 v[20:23], v142 offset:4096
	s_waitcnt lgkmcnt(0)
	v_mfma_f32_16x16x32_bf16 v[16:19], v[20:23], v[8:11], v[16:19]
	ds_read_b128 v[20:23], v143 offset:4096
	s_waitcnt lgkmcnt(0)
	v_mfma_f32_16x16x32_bf16 v[40:43], v[20:23], v[12:15], v[16:19]
	ds_read_b128 v[20:23], v140 offset:8192
	s_nop 3
	v_pk_fma_f32 v[18:19], v[54:55], s[66:67], v[56:57] op_sel_hi:[0,1,0]
	s_mov_b32 s66, 0x42000000
	s_mov_b32 s67, 0x42040000
	v_pk_fma_f32 v[16:17], v[54:55], s[66:67], v[56:57] op_sel_hi:[0,1,0]
	s_mov_b32 s66, 0x42480000
	s_mov_b32 s67, 0x424c0000
	s_waitcnt lgkmcnt(0)
	v_mfma_f32_16x16x32_bf16 v[16:19], v[20:23], v[0:3], v[16:19]
	ds_read_b128 v[20:23], v141 offset:8192
	s_waitcnt lgkmcnt(0)
	v_mfma_f32_16x16x32_bf16 v[16:19], v[20:23], v[4:7], v[16:19]
	ds_read_b128 v[20:23], v142 offset:8192
	s_waitcnt lgkmcnt(0)
	v_mfma_f32_16x16x32_bf16 v[16:19], v[20:23], v[8:11], v[16:19]
	ds_read_b128 v[20:23], v143 offset:8192
	s_waitcnt lgkmcnt(0)
	v_mfma_f32_16x16x32_bf16 v[36:39], v[20:23], v[12:15], v[16:19]
	ds_read_b128 v[20:23], v140 offset:12288
	s_nop 3
	v_pk_fma_f32 v[18:19], v[54:55], s[66:67], v[56:57] op_sel_hi:[0,1,0]
	s_mov_b32 s66, 0x42400000
	s_mov_b32 s67, 0x42440000
	v_pk_fma_f32 v[16:17], v[54:55], s[66:67], v[56:57] op_sel_hi:[0,1,0]
	s_mov_b32 s66, 0x42800000
	s_mov_b32 s67, 0x42820000
	s_waitcnt lgkmcnt(0)
	v_mfma_f32_16x16x32_bf16 v[16:19], v[20:23], v[0:3], v[16:19]
	ds_read_b128 v[20:23], v141 offset:12288
	s_waitcnt lgkmcnt(0)
	v_mfma_f32_16x16x32_bf16 v[16:19], v[20:23], v[4:7], v[16:19]
	ds_read_b128 v[20:23], v142 offset:12288
	s_waitcnt lgkmcnt(0)
	v_mfma_f32_16x16x32_bf16 v[16:19], v[20:23], v[8:11], v[16:19]
	ds_read_b128 v[20:23], v143 offset:12288
	s_waitcnt lgkmcnt(0)
	v_mfma_f32_16x16x32_bf16 v[32:35], v[20:23], v[12:15], v[16:19]
	ds_read_b128 v[20:23], v140 offset:16384
	s_nop 3
	v_pk_fma_f32 v[18:19], v[54:55], s[70:71], v[56:57] op_sel_hi:[0,1,0]
	v_pk_fma_f32 v[16:17], v[54:55], s[66:67], v[56:57] op_sel_hi:[0,1,0]
	s_and_b32 s66, s62, 15
	s_waitcnt lgkmcnt(0)
	v_mfma_f32_16x16x32_bf16 v[16:19], v[20:23], v[0:3], v[16:19]
	ds_read_b128 v[20:23], v141 offset:16384
	s_waitcnt lgkmcnt(0)
	v_mfma_f32_16x16x32_bf16 v[16:19], v[20:23], v[4:7], v[16:19]
	ds_read_b128 v[20:23], v142 offset:16384
	s_waitcnt lgkmcnt(0)
	v_mfma_f32_16x16x32_bf16 v[16:19], v[20:23], v[8:11], v[16:19]
	ds_read_b128 v[20:23], v143 offset:16384
	s_waitcnt lgkmcnt(0)
	v_mfma_f32_16x16x32_bf16 v[28:31], v[20:23], v[12:15], v[16:19]
	ds_read_b128 v[20:23], v140 offset:20480
	s_nop 3
	v_pk_fma_f32 v[18:19], v[54:55], s[72:73], v[56:57] op_sel_hi:[0,1,0]
	v_pk_fma_f32 v[16:17], v[54:55], s[74:75], v[56:57] op_sel_hi:[0,1,0]
	s_waitcnt lgkmcnt(0)
	s_nop 0
	v_mfma_f32_16x16x32_bf16 v[16:19], v[20:23], v[0:3], v[16:19]
	ds_read_b128 v[20:23], v141 offset:20480
	s_waitcnt lgkmcnt(0)
; #define LAS __attribute__((address_space(3)))
; #define WG_BAR() do { asm volatile("s_waitcnt lgkmcnt(0)" ::: "memory"); __builtin_amdgcn_s_barrier(); asm volatile("" ::: "memory"); } while (0)
; template <int MODE, class Dec>
; __device__ __forceinline__ void attn_phase(const Frame& F, const bf16* Q, const bf16* K, const bf16* V, int nunits, const Dec dec, const bf16* O3, const float* L2, const float* L3) {
;     ...
;         for (int tt = 0; tt < 9; ++tt) {
;             s[tt] = (f32x4){fmaf(sl, (float)(16 * tt), cb), fmaf(sl, (float)(16 * tt + 1), cb), fmaf(sl, (float)(16 * tt + 2), cb), fmaf(sl, (float)(16 * tt + 3), cb)};
; #pragma unroll
;             for (int ks = 0; ks < 4; ++ks) { const bf16x8 a = *(const LAS bf16x8*)(kb + ksw[ks] + tt * 4096); s[tt] = __builtin_amdgcn_mfma_f32_16x16x32_bf16(a, qf[ks], s[tt], 0, 0, 0); }
;         }
;         __builtin_amdgcn_s_setprio(0);
;         WG_BAR();
;         v2u a2[8], a3[8]; float l2v = 0.f, l3v = 0.f;
;         bf16* op = cur.Og + qrow * (size_t)cur.ldo + h * 128 + 4 * g;
;         if (MODE == 1) { const bf16* o3p = O3 + qrow * 2048 + h * 128 + 4 * g;
; #pragma unroll
;             for (int dt = 0; dt < 8; ++dt) { a2[dt] = *(const v2u*)(op + 16 * dt); a3[dt] = *(const v2u*)(o3p + 16 * dt); }
;             l2v = L2[qrow * 16 + h]; l3v = L3[qrow * 16 + h]; }
;         if (has_next) { attn_issue<false>(F, K, nxt, 0);
;             q_load4(Q + (size_t)(nxt.b * SEQ + (nxt.n * 128 + qi) * nxt.d + nxt.r) * 2048 + nxt.h * 128 + 8 * g, qn); }
	v_mfma_f32_16x16x32_bf16 v[16:19], v[20:23], v[4:7], v[16:19]
	ds_read_b128 v[20:23], v142 offset:20480
	s_waitcnt lgkmcnt(0)
	v_mfma_f32_16x16x32_bf16 v[16:19], v[20:23], v[8:11], v[16:19]
	ds_read_b128 v[20:23], v143 offset:20480
	s_waitcnt lgkmcnt(0)
	v_mfma_f32_16x16x32_bf16 v[24:27], v[20:23], v[12:15], v[16:19]
	ds_read_b128 v[20:23], v140 offset:24576
	s_nop 3
	v_pk_fma_f32 v[18:19], v[54:55], s[76:77], v[56:57] op_sel_hi:[0,1,0]
	v_pk_fma_f32 v[16:17], v[54:55], s[80:81], v[56:57] op_sel_hi:[0,1,0]
	s_waitcnt lgkmcnt(0)
	s_nop 0
	v_mfma_f32_16x16x32_bf16 v[16:19], v[20:23], v[0:3], v[16:19]
	ds_read_b128 v[20:23], v141 offset:24576
	s_waitcnt lgkmcnt(0)
	v_mfma_f32_16x16x32_bf16 v[16:19], v[20:23], v[4:7], v[16:19]
	ds_read_b128 v[20:23], v142 offset:24576
	s_waitcnt lgkmcnt(0)
	v_mfma_f32_16x16x32_bf16 v[16:19], v[20:23], v[8:11], v[16:19]
	ds_read_b128 v[20:23], v143 offset:24576
	s_waitcnt lgkmcnt(0)
	v_mfma_f32_16x16x32_bf16 v[20:23], v[20:23], v[12:15], v[16:19]
	s_nop 4
	v_fma_f32 v18, v54, s96, v56
	v_fma_f32 v19, v54, s97, v56
	v_pk_fma_f32 v[16:17], v[54:55], s[94:95], v[56:57] op_sel_hi:[0,1,0]
	s_nop 1
	v_mfma_f32_16x16x32_bf16 v[16:19], v[48:51], v[0:3], v[16:19]
	ds_read_b128 v[48:51], v141 offset:28672
	s_waitcnt lgkmcnt(0)
	v_mfma_f32_16x16x32_bf16 v[16:19], v[48:51], v[4:7], v[16:19]
	ds_read_b128 v[48:51], v142 offset:28672
	s_waitcnt lgkmcnt(0)
	v_mfma_f32_16x16x32_bf16 v[16:19], v[48:51], v[8:11], v[16:19]
	ds_read_b128 v[48:51], v143 offset:28672
	s_waitcnt lgkmcnt(0)
	v_mfma_f32_16x16x32_bf16 v[16:19], v[48:51], v[12:15], v[16:19]
	v_fma_f32 v50, v54, s78, v56
	v_fma_f32 v51, v54, s79, v56
	v_pk_fma_f32 v[48:49], v[54:55], s[82:83], v[56:57] op_sel_hi:[0,1,0]
	ds_read_b128 v[54:57], v140 offset:32768
	s_waitcnt lgkmcnt(0)
	v_mfma_f32_16x16x32_bf16 v[48:51], v[54:57], v[0:3], v[48:51]
	ds_read_b128 v[54:57], v141 offset:32768
	s_waitcnt lgkmcnt(0)
	v_mfma_f32_16x16x32_bf16 v[48:51], v[54:57], v[4:7], v[48:51]
	ds_read_b128 v[54:57], v142 offset:32768
	s_waitcnt lgkmcnt(0)
	v_mfma_f32_16x16x32_bf16 v[48:51], v[54:57], v[8:11], v[48:51]
	ds_read_b128 v[54:57], v143 offset:32768
	s_waitcnt lgkmcnt(0)
	v_mfma_f32_16x16x32_bf16 v[48:51], v[54:57], v[12:15], v[48:51]
	s_nop 0
	v_lshlrev_b64 v[54:55], 13, v[52:53]
	v_lshl_add_u64 v[54:55], s[86:87], 0, v[54:55]
	s_lshl_b32 s48, s92, 8
	v_lshl_add_u64 v[54:55], v[54:55], 0, s[48:49]
	v_lshl_add_u64 v[92:93], v[54:55], 0, v[74:75]
	v_lshlrev_b64 v[54:55], 12, v[52:53]
	v_lshl_add_u64 v[54:55], s[42:43], 0, v[54:55]
	s_waitcnt lgkmcnt(0)
	s_barrier
	v_lshl_add_u64 v[54:55], v[54:55], 0, s[48:49]
	v_lshl_add_u64 v[54:55], v[54:55], 0, v[74:75]
	v_bfe_u32 v242, v156, 4, 1
	v_mul_u32_u24_e32 v242, 24, v242
	v_mov_b32_e32 v243, 0
	v_lshl_add_u64 v[240:241], v[92:93], 0, v[242:243]
	v_lshl_add_u64 v[244:245], v[54:55], 0, v[242:243]
	global_load_dwordx4 v[94:97], v[240:241], off
	global_load_dwordx4 v[98:101], v[244:245], off
	global_load_dwordx4 v[102:105], v[240:241], off offset:64
	global_load_dwordx4 v[106:109], v[244:245], off offset:64
	global_load_dwordx4 v[110:113], v[240:241], off offset:128
	global_load_dwordx4 v[114:117], v[244:245], off offset:128
	global_load_dwordx4 v[118:121], v[240:241], off offset:192
	global_load_dwordx4 v[122:125], v[244:245], off offset:192
	s_mov_b32 s93, s49
	v_lshlrev_b64 v[52:53], 6, v[52:53]
	s_lshl_b64 s[68:69], s[92:93], 2
	v_or_b32_e32 v53, s69, v53
	v_or_b32_e32 v52, s68, v52
	v_lshl_add_u64 v[54:55], s[44:45], 0, v[52:53]
	v_lshl_add_u64 v[52:53], s[46:47], 0, v[52:53]
	global_load_dword v147, v[54:55], off
	global_load_dword v148, v[52:53], off
	s_and_b64 vcc, exec, s[2:3]
	s_cbranch_vccnz .LBB0_544
	s_lshl_b32 s67, s64, 11
	s_cmp_lg_u32 s66, 0
	s_cbranch_scc0 .LBB0_555
	s_lshl_b32 s68, s66, 7
	s_add_i32 s48, s68, s67
	s_add_i32 s69, s48, 0xffffff80
	v_add_u32_e32 v0, s69, v127
	v_ashrrev_i32_e32 v1, 31, v0
	v_lshlrev_b64 v[0:1], 11, v[0:1]
	s_lshl_b32 s48, s34, 7
	v_or_b32_e32 v0, v0, v82
	v_or_b32_e32 v0, s48, v0
	v_lshl_add_u64 v[0:1], v[0:1], 1, s[36:37]
	s_add_i32 m0, s35, 0
	s_nop 0
	global_load_lds_dwordx4 v[0:1], off
	v_add_u32_e32 v0, s69, v126
	v_ashrrev_i32_e32 v1, 31, v0
	v_lshlrev_b64 v[0:1], 11, v[0:1]
	v_or_b32_e32 v0, v0, v84
	v_or_b32_e32 v0, s48, v0
	v_lshl_add_u64 v[0:1], v[0:1], 1, s[36:37]
	s_add_i32 m0, s54, 0
	s_nop 0
	global_load_lds_dwordx4 v[0:1], off
	v_add_u32_e32 v0, s69, v128
	v_ashrrev_i32_e32 v1, 31, v0
	v_lshlrev_b64 v[0:1], 11, v[0:1]
	v_or_b32_e32 v0, v0, v86
	v_or_b32_e32 v0, s48, v0
	v_lshl_add_u64 v[0:1], v[0:1], 1, s[36:37]
	s_add_i32 m0, s55, 0
	s_nop 0
	global_load_lds_dwordx4 v[0:1], off
	v_add_u32_e32 v0, s69, v129
	v_ashrrev_i32_e32 v1, 31, v0
	v_lshlrev_b64 v[0:1], 11, v[0:1]
	v_or_b32_e32 v0, v0, v88
	v_or_b32_e32 v0, s48, v0
	v_lshl_add_u64 v[0:1], v[0:1], 1, s[36:37]
	s_add_i32 m0, s56, 0
	s_nop 0
	global_load_lds_dwordx4 v[0:1], off
	s_cbranch_execnz .LBB0_543

; #define WG_BAR() do { asm volatile("s_waitcnt lgkmcnt(0)" ::: "memory"); __builtin_amdgcn_s_barrier(); asm volatile("" ::: "memory"); } while (0)
; template <int MODE, class Dec>
; __device__ __forceinline__ void attn_phase(const Frame& F, const bf16* Q, const bf16* K, const bf16* V, int nunits, const Dec dec, const bf16* O3, const float* L2, const float* L3) {
;     ...
;         WG_BAR();
;         f32x4 o[8];
;         s16x4 vfa[10], vfb[10];
;         tr_issue10((unsigned)(size_t)(vb + (((p4 >> 1)) ^ frl) * 16), vfa);
; #pragma unroll
;         for (int dt = 0; dt < 8; dt += 2) {
;             tr_issue10((unsigned)(size_t)(vb + (((2 * (dt + 1) + (p4 >> 1)) ^ frl) << 4)), vfb);
;             tr_wait10<10>(vfa);
;             __builtin_amdgcn_s_setprio(1);
;             o[dt] = (f32x4){0.f, 0.f, 0.f, 0.f};
; #pragma unroll
;             for (int pp = 0; pp < 5; ++pp) { const bf16x8 a = __builtin_shufflevector(vfa[2 * pp], vfa[2 * pp + 1], 0, 1, 2, 3, 4, 5, 6, 7);
;                 o[dt] = __builtin_amdgcn_mfma_f32_16x16x32_bf16(a, pf[pp], o[dt], 0, 0, 0); }
;             __builtin_amdgcn_s_setprio(0);
;             if (dt + 2 < 8) { tr_issue10((unsigned)(size_t)(vb + (((2 * (dt + 2) + (p4 >> 1)) ^ frl) << 4)), vfa); tr_wait10<10>(vfb); } else tr_wait10<0>(vfb);
;             __builtin_amdgcn_s_setprio(1);
;             o[dt + 1] = (f32x4){0.f, 0.f, 0.f, 0.f};
; #pragma unroll
;             for (int pp = 0; pp < 5; ++pp) { const bf16x8 a = __builtin_shufflevector(vfb[2 * pp], vfb[2 * pp + 1], 0, 1, 2, 3, 4, 5, 6, 7);
;                 o[dt + 1] = __builtin_amdgcn_mfma_f32_16x16x32_bf16(a, pf[pp], o[dt + 1], 0, 0, 0); }
;             __builtin_amdgcn_s_setprio(0);
;         }
;         WG_BAR();
.LBB0_552:
	s_waitcnt lgkmcnt(0)
	s_barrier
	s_waitcnt lgkmcnt(0)
	v_add_f32_e32 v149, v16, v17
	ds_read_b64_tr_b16 v[32:33], v132
	ds_read_b64_tr_b16 v[34:35], v132 offset:4096
	ds_read_b64_tr_b16 v[28:29], v132 offset:8192
	ds_read_b64_tr_b16 v[30:31], v132 offset:12288
	ds_read_b64_tr_b16 v[24:25], v132 offset:16384
	ds_read_b64_tr_b16 v[26:27], v132 offset:20480
	ds_read_b64_tr_b16 v[20:21], v132 offset:24576
	ds_read_b64_tr_b16 v[22:23], v132 offset:28672
	ds_read_b64_tr_b16 v[16:17], v132 offset:32768
	ds_read_b64_tr_b16 v[18:19], v132 offset:32768
	ds_read_b64_tr_b16 v[162:163], v133
	ds_read_b64_tr_b16 v[164:165], v133 offset:4096
	ds_read_b64_tr_b16 v[158:159], v133 offset:8192
	ds_read_b64_tr_b16 v[160:161], v133 offset:12288
	ds_read_b64_tr_b16 v[150:151], v133 offset:16384
	ds_read_b64_tr_b16 v[152:153], v133 offset:20480
	ds_read_b64_tr_b16 v[40:41], v133 offset:24576
	ds_read_b64_tr_b16 v[42:43], v133 offset:28672
	ds_read_b64_tr_b16 v[36:37], v133 offset:32768
	ds_read_b64_tr_b16 v[38:39], v133 offset:32768
	s_nop 0
	s_waitcnt lgkmcnt(10)
	s_nop 0
	v_mfma_f32_16x16x32_bf16 v[32:35], v[32:35], v[60:63], 0
	v_mfma_f32_16x16x32_bf16 v[28:31], v[28:31], v[56:59], v[32:35]
	v_mfma_f32_16x16x32_bf16 v[24:27], v[24:27], v[52:55], v[28:31]
	v_mfma_f32_16x16x32_bf16 v[20:23], v[20:23], v[48:51], v[24:27]
	v_mfma_f32_16x16x32_bf16 v[16:19], v[16:19], v[44:47], v[20:23]
	s_nop 0
	ds_read_b64_tr_b16 v[170:171], v134
	ds_read_b64_tr_b16 v[172:173], v134 offset:4096
	ds_read_b64_tr_b16 v[166:167], v134 offset:8192
	ds_read_b64_tr_b16 v[168:169], v134 offset:12288
	ds_read_b64_tr_b16 v[32:33], v134 offset:16384
	ds_read_b64_tr_b16 v[34:35], v134 offset:20480
	ds_read_b64_tr_b16 v[28:29], v134 offset:24576
	ds_read_b64_tr_b16 v[30:31], v134 offset:28672
	ds_read_b64_tr_b16 v[24:25], v134 offset:32768
	ds_read_b64_tr_b16 v[26:27], v134 offset:32768
	s_waitcnt lgkmcnt(10)
	s_nop 0
	v_mfma_f32_16x16x32_bf16 v[20:23], v[162:165], v[60:63], 0
	v_mfma_f32_16x16x32_bf16 v[20:23], v[158:161], v[56:59], v[20:23]
	v_mfma_f32_16x16x32_bf16 v[20:23], v[150:153], v[52:55], v[20:23]
	v_mfma_f32_16x16x32_bf16 v[20:23], v[40:43], v[48:51], v[20:23]
	v_mfma_f32_16x16x32_bf16 v[20:23], v[36:39], v[44:47], v[20:23]
	s_nop 0
	ds_read_b64_tr_b16 v[162:163], v135
	ds_read_b64_tr_b16 v[164:165], v135 offset:4096
	ds_read_b64_tr_b16 v[158:159], v135 offset:8192
	ds_read_b64_tr_b16 v[160:161], v135 offset:12288
	ds_read_b64_tr_b16 v[150:151], v135 offset:16384
	ds_read_b64_tr_b16 v[152:153], v135 offset:20480
	ds_read_b64_tr_b16 v[40:41], v135 offset:24576
	ds_read_b64_tr_b16 v[42:43], v135 offset:28672
	ds_read_b64_tr_b16 v[36:37], v135 offset:32768
	ds_read_b64_tr_b16 v[38:39], v135 offset:32768
	s_waitcnt lgkmcnt(10)
	s_nop 0
	v_mfma_f32_16x16x32_bf16 v[170:173], v[170:173], v[60:63], 0
	v_mfma_f32_16x16x32_bf16 v[166:169], v[166:169], v[56:59], v[170:173]
	v_mfma_f32_16x16x32_bf16 v[32:35], v[32:35], v[52:55], v[166:169]
	v_mfma_f32_16x16x32_bf16 v[28:31], v[28:31], v[48:51], v[32:35]
	v_mfma_f32_16x16x32_bf16 v[24:27], v[24:27], v[44:47], v[28:31]
	s_nop 0
	ds_read_b64_tr_b16 v[178:179], v136
	ds_read_b64_tr_b16 v[180:181], v136 offset:4096
	ds_read_b64_tr_b16 v[174:175], v136 offset:8192
	ds_read_b64_tr_b16 v[176:177], v136 offset:12288
	ds_read_b64_tr_b16 v[170:171], v136 offset:16384
	ds_read_b64_tr_b16 v[172:173], v136 offset:20480
	ds_read_b64_tr_b16 v[166:167], v136 offset:24576
	ds_read_b64_tr_b16 v[168:169], v136 offset:28672
	ds_read_b64_tr_b16 v[32:33], v136 offset:32768
	ds_read_b64_tr_b16 v[34:35], v136 offset:32768
	s_waitcnt lgkmcnt(10)
	s_nop 0
	v_mfma_f32_16x16x32_bf16 v[28:31], v[162:165], v[60:63], 0
	v_mfma_f32_16x16x32_bf16 v[28:31], v[158:161], v[56:59], v[28:31]
	v_mfma_f32_16x16x32_bf16 v[28:31], v[150:153], v[52:55], v[28:31]
	v_mfma_f32_16x16x32_bf16 v[28:31], v[40:43], v[48:51], v[28:31]
	v_mfma_f32_16x16x32_bf16 v[28:31], v[36:39], v[44:47], v[28:31]
	s_nop 0
	ds_read_b64_tr_b16 v[162:163], v137
	ds_read_b64_tr_b16 v[164:165], v137 offset:4096
	ds_read_b64_tr_b16 v[158:159], v137 offset:8192
	ds_read_b64_tr_b16 v[160:161], v137 offset:12288
	ds_read_b64_tr_b16 v[150:151], v137 offset:16384
	ds_read_b64_tr_b16 v[152:153], v137 offset:20480
	ds_read_b64_tr_b16 v[40:41], v137 offset:24576
	ds_read_b64_tr_b16 v[42:43], v137 offset:28672
	ds_read_b64_tr_b16 v[36:37], v137 offset:32768
	ds_read_b64_tr_b16 v[38:39], v137 offset:32768
	s_waitcnt lgkmcnt(10)
	s_nop 0
	v_mfma_f32_16x16x32_bf16 v[178:181], v[178:181], v[60:63], 0
	v_mfma_f32_16x16x32_bf16 v[174:177], v[174:177], v[56:59], v[178:181]
	v_mfma_f32_16x16x32_bf16 v[170:173], v[170:173], v[52:55], v[174:177]
	v_mfma_f32_16x16x32_bf16 v[166:169], v[166:169], v[48:51], v[170:173]
	v_mfma_f32_16x16x32_bf16 v[32:35], v[32:35], v[44:47], v[166:169]
	s_nop 0
	ds_read_b64_tr_b16 v[182:183], v138
	ds_read_b64_tr_b16 v[184:185], v138 offset:4096
	ds_read_b64_tr_b16 v[178:179], v138 offset:8192
	ds_read_b64_tr_b16 v[180:181], v138 offset:12288
	ds_read_b64_tr_b16 v[174:175], v138 offset:16384
	ds_read_b64_tr_b16 v[176:177], v138 offset:20480
	ds_read_b64_tr_b16 v[170:171], v138 offset:24576
	ds_read_b64_tr_b16 v[172:173], v138 offset:28672
	ds_read_b64_tr_b16 v[166:167], v138 offset:32768
	ds_read_b64_tr_b16 v[168:169], v138 offset:32768
	s_waitcnt lgkmcnt(10)
	s_nop 0
	v_mfma_f32_16x16x32_bf16 v[162:165], v[162:165], v[60:63], 0
	v_mfma_f32_16x16x32_bf16 v[158:161], v[158:161], v[56:59], v[162:165]
	v_mfma_f32_16x16x32_bf16 v[150:153], v[150:153], v[52:55], v[158:161]
	v_mfma_f32_16x16x32_bf16 v[40:43], v[40:43], v[48:51], v[150:153]
	v_mfma_f32_16x16x32_bf16 v[36:39], v[36:39], v[44:47], v[40:43]
	s_nop 0
	ds_read_b64_tr_b16 v[190:191], v139
	ds_read_b64_tr_b16 v[192:193], v139 offset:4096
	ds_read_b64_tr_b16 v[186:187], v139 offset:8192
	ds_read_b64_tr_b16 v[188:189], v139 offset:12288
	ds_read_b64_tr_b16 v[162:163], v139 offset:16384
	ds_read_b64_tr_b16 v[164:165], v139 offset:20480
	ds_read_b64_tr_b16 v[158:159], v139 offset:24576
	ds_read_b64_tr_b16 v[160:161], v139 offset:28672
	ds_read_b64_tr_b16 v[150:151], v139 offset:32768
	ds_read_b64_tr_b16 v[152:153], v139 offset:32768
	s_waitcnt lgkmcnt(10)
	s_nop 0
	v_mfma_f32_16x16x32_bf16 v[40:43], v[182:185], v[60:63], 0
	v_mfma_f32_16x16x32_bf16 v[40:43], v[178:181], v[56:59], v[40:43]
	v_mfma_f32_16x16x32_bf16 v[40:43], v[174:177], v[52:55], v[40:43]
	v_mfma_f32_16x16x32_bf16 v[40:43], v[170:173], v[48:51], v[40:43]
	v_mfma_f32_16x16x32_bf16 v[40:43], v[166:169], v[44:47], v[40:43]
	s_nop 0
	s_waitcnt lgkmcnt(0)
	s_nop 0
	v_mfma_f32_16x16x32_bf16 v[60:63], v[190:193], v[60:63], 0
	v_mfma_f32_16x16x32_bf16 v[56:59], v[186:189], v[56:59], v[60:63]
	v_mfma_f32_16x16x32_bf16 v[52:55], v[162:165], v[52:55], v[56:59]
	v_mfma_f32_16x16x32_bf16 v[48:51], v[158:161], v[48:51], v[52:55]
	v_mfma_f32_16x16x32_bf16 v[44:47], v[150:153], v[44:47], v[48:51]
	s_nop 0
	s_nop 5
	v_div_scale_f32 v48, s[2:3], v149, v149, 1.0
	v_rcp_f32_e32 v49, v48
	s_waitcnt lgkmcnt(0)
	s_barrier
; __device__ __forceinline__ unsigned cvt_pk_bf16(float lo, float hi) { unsigned r; asm volatile("v_cvt_pk_bf16_f32 %0, %1, %2" : "=v"(r) : "v"(lo), "v"(hi)); return r; }
; __device__ __forceinline__ float bf_lo(unsigned w) { return __uint_as_float(w << 16); }
; __device__ __forceinline__ float bf_hi(unsigned w) { return __uint_as_float(w & 0xffff0000u); }
; template <int MODE, class Dec>
; __device__ __forceinline__ void attn_phase(const Frame& F, const bf16* Q, const bf16* K, const bf16* V, int nunits, const Dec dec, const bf16* O3, const float* L2, const float* L3) {
;     ...
;         const float linv = 1.0f / l, lse = mx + __builtin_amdgcn_logf(l);
;         if (MODE == 0) {
; #pragma unroll
;             for (int dt = 0; dt < 8; ++dt) { v2u wv; wv.x = pg8::cvt_pk_bf16(o[dt][0] * linv, o[dt][1] * linv); wv.y = pg8::cvt_pk_bf16(o[dt][2] * linv, o[dt][3] * linv); *(v2u*)(op + 16 * dt) = wv; }
;             if (g == 0) cur.Lg[qrow * 16 + h] = lse;
;         } else {
;             const float mm = fmaxf(lse, fmaxf(l2v, l3v));
;             float w1 = __builtin_amdgcn_exp2f(lse - mm), w2 = __builtin_amdgcn_exp2f(l2v - mm), w3 = __builtin_amdgcn_exp2f(l3v - mm); const float wi = 1.0f / (w1 + w2 + w3);
;             w1 *= wi * linv; w2 *= wi; w3 *= wi;
; #pragma unroll
;             for (int dt = 0; dt < 8; ++dt) {
;                 const float y0 = w1 * o[dt][0] + w2 * pg8::bf_lo(a2[dt].x) + w3 * pg8::bf_lo(a3[dt].x), y1 = w1 * o[dt][1] + w2 * pg8::bf_hi(a2[dt].x) + w3 * pg8::bf_hi(a3[dt].x);
;                 const float y2 = w1 * o[dt][2] + w2 * pg8::bf_lo(a2[dt].y) + w3 * pg8::bf_lo(a3[dt].y), y3 = w1 * o[dt][3] + w2 * pg8::bf_hi(a2[dt].y) + w3 * pg8::bf_hi(a3[dt].y);
;                 v2u wv; wv.x = pg8::cvt_pk_bf16(y0, y1); wv.y = pg8::cvt_pk_bf16(y2, y3); *(v2u*)(op + 16 * dt) = wv; }
	v_fma_f32 v50, -v48, v49, 1.0
	v_fmac_f32_e32 v49, v50, v49
	v_div_scale_f32 v50, vcc, 1.0, v149, 1.0
	v_mul_f32_e32 v51, v50, v49
	v_fma_f32 v52, -v48, v51, v50
	v_fmac_f32_e32 v51, v52, v49
	v_fma_f32 v48, -v48, v51, v50
	v_div_fmas_f32 v48, v48, v49, v51
	v_div_fixup_f32 v51, v48, v149, 1.0
	v_log_f32_e32 v48, v149
	s_waitcnt vmcnt(0)
	s_nop 0
	v_add_f32_e32 v48, v91, v48
	s_waitcnt vmcnt(0)
	v_permlane16_swap_b32 v94, v96
	v_permlane16_swap_b32 v95, v97
	v_permlane16_swap_b32 v102, v104
	v_permlane16_swap_b32 v103, v105
	v_permlane16_swap_b32 v110, v112
	v_permlane16_swap_b32 v111, v113
	v_permlane16_swap_b32 v118, v120
	v_permlane16_swap_b32 v119, v121
	v_permlane16_swap_b32 v98, v100
	v_permlane16_swap_b32 v99, v101
	v_permlane16_swap_b32 v106, v108
	v_permlane16_swap_b32 v107, v109
	v_permlane16_swap_b32 v114, v116
	v_permlane16_swap_b32 v115, v117
	v_permlane16_swap_b32 v122, v124
	v_permlane16_swap_b32 v123, v125
	v_max3_f32 v50, v48, v147, v148
	v_sub_f32_e32 v48, v48, v50
	v_exp_f32_e32 v52, v48
	v_sub_f32_e32 v48, v147, v50
	v_exp_f32_e32 v49, v48
	v_sub_f32_e32 v48, v148, v50
	v_exp_f32_e32 v48, v48
	v_add_f32_e32 v50, v52, v49
	v_add_f32_e32 v50, v48, v50
	v_div_scale_f32 v53, s[2:3], v50, v50, 1.0
	v_rcp_f32_e32 v54, v53
	s_mov_b64 s[2:3], -1
	v_fma_f32 v55, -v53, v54, 1.0
	v_fmac_f32_e32 v54, v55, v54
	v_div_scale_f32 v55, vcc, 1.0, v50, 1.0
	v_mul_f32_e32 v56, v55, v54
	v_fma_f32 v57, -v53, v56, v55
	v_fmac_f32_e32 v56, v57, v54
	v_fma_f32 v53, -v53, v56, v55
	v_div_fmas_f32 v53, v53, v54, v56
	v_div_fixup_f32 v50, v53, v50, 1.0
	v_mul_f32_e32 v51, v51, v50
	v_mul_f32_e32 v52, v52, v51
	v_pk_mul_f32 v[48:49], v[48:49], v[50:51] op_sel_hi:[1,0]
	v_lshlrev_b32_e32 v51, 16, v94
	v_lshlrev_b32_e32 v50, 16, v98
	v_pk_mul_f32 v[50:51], v[48:49], v[50:51]
	s_andn2_b64 vcc, exec, s[50:51]
	v_fma_f32 v16, v52, v16, v51
	v_add_f32_e32 v53, v50, v16
	v_and_b32_e32 v51, 0xffff0000, v94
	v_and_b32_e32 v50, 0xffff0000, v98
	v_pk_mul_f32 v[50:51], v[48:49], v[50:51]
	s_nop 0
	v_fma_f32 v16, v52, v17, v51
	v_add_f32_e32 v50, v50, v16
	v_lshlrev_b32_e32 v17, 16, v95
	v_lshlrev_b32_e32 v16, 16, v99
	v_pk_mul_f32 v[16:17], v[48:49], v[16:17]
	s_nop 0
	v_fma_f32 v17, v52, v18, v17
	v_add_f32_e32 v18, v16, v17
	v_and_b32_e32 v17, 0xffff0000, v95
	v_and_b32_e32 v16, 0xffff0000, v99
	v_pk_mul_f32 v[16:17], v[48:49], v[16:17]
	s_nop 0
	v_fma_f32 v17, v52, v19, v17
	v_add_f32_e32 v17, v16, v17
	v_cvt_pk_bf16_f32 v16, v53, v50
	v_cvt_pk_bf16_f32 v17, v18, v17
	v_mov_b32_e32 v236, v16
	v_mov_b32_e32 v237, v17
	v_lshlrev_b32_e32 v17, 16, v96
	v_lshlrev_b32_e32 v16, 16, v100
	v_pk_mul_f32 v[16:17], v[48:49], v[16:17]
	s_nop 0
	v_fma_f32 v17, v52, v20, v17
	v_add_f32_e32 v18, v16, v17
	v_and_b32_e32 v17, 0xffff0000, v96
	v_and_b32_e32 v16, 0xffff0000, v100
	v_pk_mul_f32 v[16:17], v[48:49], v[16:17]
	s_nop 0
	v_fma_f32 v17, v52, v21, v17
	v_add_f32_e32 v19, v16, v17
	v_lshlrev_b32_e32 v17, 16, v97
	v_lshlrev_b32_e32 v16, 16, v101
	v_pk_mul_f32 v[16:17], v[48:49], v[16:17]
	s_nop 0
	v_fma_f32 v17, v52, v22, v17
	v_add_f32_e32 v20, v16, v17
	v_and_b32_e32 v17, 0xffff0000, v97
	v_and_b32_e32 v16, 0xffff0000, v101
	v_pk_mul_f32 v[16:17], v[48:49], v[16:17]
	s_nop 0
	v_fma_f32 v17, v52, v23, v17
	v_add_f32_e32 v17, v16, v17
	v_cvt_pk_bf16_f32 v16, v18, v19
	v_cvt_pk_bf16_f32 v17, v20, v17
	v_mov_b32_e32 v238, v16
	v_mov_b32_e32 v239, v17
	s_nop 1
	v_permlane16_swap_b32 v236, v238
	v_permlane16_swap_b32 v237, v239
	global_store_dwordx4 v[240:241], v[236:239], off
	v_lshlrev_b32_e32 v17, 16, v102
	v_lshlrev_b32_e32 v16, 16, v106
	v_pk_mul_f32 v[16:17], v[48:49], v[16:17]
	s_nop 0
	v_fma_f32 v17, v52, v24, v17
	v_add_f32_e32 v18, v16, v17
	v_and_b32_e32 v17, 0xffff0000, v102
	v_and_b32_e32 v16, 0xffff0000, v106
	v_pk_mul_f32 v[16:17], v[48:49], v[16:17]
	s_nop 0
	v_fma_f32 v17, v52, v25, v17
	v_add_f32_e32 v19, v16, v17
	v_lshlrev_b32_e32 v17, 16, v103
	v_lshlrev_b32_e32 v16, 16, v107
	v_pk_mul_f32 v[16:17], v[48:49], v[16:17]
	s_nop 0
	v_fma_f32 v17, v52, v26, v17
	v_add_f32_e32 v20, v16, v17
	v_and_b32_e32 v17, 0xffff0000, v103
	v_and_b32_e32 v16, 0xffff0000, v107
	v_pk_mul_f32 v[16:17], v[48:49], v[16:17]
	s_nop 0
	v_fma_f32 v17, v52, v27, v17
	v_add_f32_e32 v17, v16, v17
	v_cvt_pk_bf16_f32 v16, v18, v19
	v_cvt_pk_bf16_f32 v17, v20, v17
	v_mov_b32_e32 v236, v16
	v_mov_b32_e32 v237, v17
	v_lshlrev_b32_e32 v17, 16, v104
	v_lshlrev_b32_e32 v16, 16, v108
	v_pk_mul_f32 v[16:17], v[48:49], v[16:17]
	s_nop 0
	v_fma_f32 v17, v52, v28, v17
	v_add_f32_e32 v18, v16, v17
	v_and_b32_e32 v17, 0xffff0000, v104
	v_and_b32_e32 v16, 0xffff0000, v108
	v_pk_mul_f32 v[16:17], v[48:49], v[16:17]
	s_nop 0
	v_fma_f32 v17, v52, v29, v17
	v_add_f32_e32 v19, v16, v17
	v_lshlrev_b32_e32 v17, 16, v105
	v_lshlrev_b32_e32 v16, 16, v109
	v_pk_mul_f32 v[16:17], v[48:49], v[16:17]
	s_nop 0
	v_fma_f32 v17, v52, v30, v17
	v_add_f32_e32 v20, v16, v17
	v_and_b32_e32 v17, 0xffff0000, v105
	v_and_b32_e32 v16, 0xffff0000, v109
	v_pk_mul_f32 v[16:17], v[48:49], v[16:17]
	s_nop 0
	v_fma_f32 v17, v52, v31, v17
	v_add_f32_e32 v17, v16, v17
	v_cvt_pk_bf16_f32 v16, v18, v19
	v_cvt_pk_bf16_f32 v17, v20, v17
	v_mov_b32_e32 v238, v16
	v_mov_b32_e32 v239, v17
	s_nop 1
; __device__ __forceinline__ unsigned cvt_pk_bf16(float lo, float hi) { unsigned r; asm volatile("v_cvt_pk_bf16_f32 %0, %1, %2" : "=v"(r) : "v"(lo), "v"(hi)); return r; }
; __device__ __forceinline__ float bf_lo(unsigned w) { return __uint_as_float(w << 16); }
; __device__ __forceinline__ float bf_hi(unsigned w) { return __uint_as_float(w & 0xffff0000u); }
; #define LAS __attribute__((address_space(3)))
; template <bool VSW>
; __device__ __forceinline__ void attn_issue(const Frame& F, const bf16* X, const AUnit& a, int ldsoff) {
;     ...
;     for (int i = 0; i < 8; ++i) { const int rg = w + 8 * i, j = 4 * rg + g, jr = j & 15, c = ql ^ (VSW ? (((jr & 7) << 1) | (jr >> 3)) : jr);
;         if (i >= 4 || a.n > 0) {
;             const size_t go = ((size_t)(a.b * SEQ + ((a.n - 1) * 128 + j) * a.d + a.r) * 2048 + a.h * 128 + c * 8) * 2;
;             __builtin_amdgcn_global_load_lds((const unsigned*)((const char*)X + go), (LAS unsigned*)(F.lds + ldsoff + rg * 1024), 16, 0, 0); } }
; template <int MODE, class Dec>
; __device__ __forceinline__ void attn_phase(const Frame& F, const bf16* Q, const bf16* K, const bf16* V, int nunits, const Dec dec, const bf16* O3, const float* L2, const float* L3) {
;     ...
;                 const float y0 = w1 * o[dt][0] + w2 * pg8::bf_lo(a2[dt].x) + w3 * pg8::bf_lo(a3[dt].x), y1 = w1 * o[dt][1] + w2 * pg8::bf_hi(a2[dt].x) + w3 * pg8::bf_hi(a3[dt].x);
;                 const float y2 = w1 * o[dt][2] + w2 * pg8::bf_lo(a2[dt].y) + w3 * pg8::bf_lo(a3[dt].y), y3 = w1 * o[dt][3] + w2 * pg8::bf_hi(a2[dt].y) + w3 * pg8::bf_hi(a3[dt].y);
;                 v2u wv; wv.x = pg8::cvt_pk_bf16(y0, y1); wv.y = pg8::cvt_pk_bf16(y2, y3); *(v2u*)(op + 16 * dt) = wv; }
;         }
;         if (!has_next) break;
;         attn_issue<true>(F, V, nxt, 65536);
	v_permlane16_swap_b32 v236, v238
	v_permlane16_swap_b32 v237, v239
	global_store_dwordx4 v[240:241], v[236:239], off offset:64
	v_lshlrev_b32_e32 v17, 16, v110
	v_lshlrev_b32_e32 v16, 16, v114
	v_pk_mul_f32 v[16:17], v[48:49], v[16:17]
	s_nop 0
	v_fma_f32 v17, v52, v32, v17
	v_add_f32_e32 v18, v16, v17
	v_and_b32_e32 v17, 0xffff0000, v110
	v_and_b32_e32 v16, 0xffff0000, v114
	v_pk_mul_f32 v[16:17], v[48:49], v[16:17]
	s_nop 0
	v_fma_f32 v17, v52, v33, v17
	v_add_f32_e32 v19, v16, v17
	v_lshlrev_b32_e32 v17, 16, v111
	v_lshlrev_b32_e32 v16, 16, v115
	v_pk_mul_f32 v[16:17], v[48:49], v[16:17]
	s_nop 0
	v_fma_f32 v17, v52, v34, v17
	v_add_f32_e32 v20, v16, v17
	v_and_b32_e32 v17, 0xffff0000, v111
	v_and_b32_e32 v16, 0xffff0000, v115
	v_pk_mul_f32 v[16:17], v[48:49], v[16:17]
	s_nop 0
	v_fma_f32 v17, v52, v35, v17
	v_add_f32_e32 v17, v16, v17
	v_cvt_pk_bf16_f32 v16, v18, v19
	v_cvt_pk_bf16_f32 v17, v20, v17
	v_mov_b32_e32 v236, v16
	v_mov_b32_e32 v237, v17
	v_lshlrev_b32_e32 v17, 16, v112
	v_lshlrev_b32_e32 v16, 16, v116
	v_pk_mul_f32 v[16:17], v[48:49], v[16:17]
	s_nop 0
	v_fma_f32 v17, v52, v36, v17
	v_add_f32_e32 v18, v16, v17
	v_and_b32_e32 v17, 0xffff0000, v112
	v_and_b32_e32 v16, 0xffff0000, v116
	v_pk_mul_f32 v[16:17], v[48:49], v[16:17]
	s_nop 0
	v_fma_f32 v17, v52, v37, v17
	v_add_f32_e32 v19, v16, v17
	v_lshlrev_b32_e32 v17, 16, v113
	v_lshlrev_b32_e32 v16, 16, v117
	v_pk_mul_f32 v[16:17], v[48:49], v[16:17]
	s_nop 0
	v_fma_f32 v17, v52, v38, v17
	v_add_f32_e32 v20, v16, v17
	v_and_b32_e32 v17, 0xffff0000, v113
	v_and_b32_e32 v16, 0xffff0000, v117
	v_pk_mul_f32 v[16:17], v[48:49], v[16:17]
	s_nop 0
	v_fma_f32 v17, v52, v39, v17
	v_add_f32_e32 v17, v16, v17
	v_cvt_pk_bf16_f32 v16, v18, v19
	v_cvt_pk_bf16_f32 v17, v20, v17
	v_mov_b32_e32 v238, v16
	v_mov_b32_e32 v239, v17
	s_nop 1
	v_permlane16_swap_b32 v236, v238
	v_permlane16_swap_b32 v237, v239
	global_store_dwordx4 v[240:241], v[236:239], off offset:128
	v_lshlrev_b32_e32 v17, 16, v118
	v_lshlrev_b32_e32 v16, 16, v122
	v_pk_mul_f32 v[16:17], v[48:49], v[16:17]
	s_nop 0
	v_fma_f32 v17, v52, v40, v17
	v_add_f32_e32 v18, v16, v17
	v_and_b32_e32 v17, 0xffff0000, v118
	v_and_b32_e32 v16, 0xffff0000, v122
	v_pk_mul_f32 v[16:17], v[48:49], v[16:17]
	s_nop 0
	v_fma_f32 v17, v52, v41, v17
	v_add_f32_e32 v19, v16, v17
	v_lshlrev_b32_e32 v17, 16, v119
	v_lshlrev_b32_e32 v16, 16, v123
	v_pk_mul_f32 v[16:17], v[48:49], v[16:17]
	s_nop 0
	v_fma_f32 v17, v52, v42, v17
	v_add_f32_e32 v20, v16, v17
	v_and_b32_e32 v17, 0xffff0000, v119
	v_and_b32_e32 v16, 0xffff0000, v123
	v_pk_mul_f32 v[16:17], v[48:49], v[16:17]
	s_nop 0
	v_fma_f32 v17, v52, v43, v17
	v_add_f32_e32 v17, v16, v17
	v_cvt_pk_bf16_f32 v16, v18, v19
	v_cvt_pk_bf16_f32 v17, v20, v17
	v_mov_b32_e32 v236, v16
	v_mov_b32_e32 v237, v17
	v_lshlrev_b32_e32 v17, 16, v120
	v_lshlrev_b32_e32 v16, 16, v124
	v_pk_mul_f32 v[16:17], v[48:49], v[16:17]
	s_nop 0
	v_fma_f32 v17, v52, v44, v17
	v_add_f32_e32 v18, v16, v17
	v_and_b32_e32 v17, 0xffff0000, v120
	v_and_b32_e32 v16, 0xffff0000, v124
	v_pk_mul_f32 v[16:17], v[48:49], v[16:17]
	s_nop 0
	v_fma_f32 v17, v52, v45, v17
	v_add_f32_e32 v19, v16, v17
	v_lshlrev_b32_e32 v17, 16, v121
	v_lshlrev_b32_e32 v16, 16, v125
	v_pk_mul_f32 v[16:17], v[48:49], v[16:17]
	s_nop 0
	v_fma_f32 v17, v52, v46, v17
	v_add_f32_e32 v20, v16, v17
	v_and_b32_e32 v17, 0xffff0000, v121
	v_and_b32_e32 v16, 0xffff0000, v125
	v_pk_mul_f32 v[16:17], v[48:49], v[16:17]
	s_nop 0
	v_fma_f32 v17, v52, v47, v17
	v_add_f32_e32 v17, v16, v17
	v_cvt_pk_bf16_f32 v16, v18, v19
	v_cvt_pk_bf16_f32 v17, v20, v17
	v_mov_b32_e32 v238, v16
	v_mov_b32_e32 v239, v17
	s_nop 1
	v_permlane16_swap_b32 v236, v238
	v_permlane16_swap_b32 v237, v239
	global_store_dwordx4 v[240:241], v[236:239], off offset:192
	s_cbranch_vccnz .LBB0_538
	s_lshl_b32 s51, s64, 11
	s_cmp_lg_u32 s66, 0
	s_cbranch_scc0 .LBB0_557
	s_lshl_b32 s2, s66, 7
	s_add_i32 s2, s2, s51
	s_add_i32 s50, s2, 0xffffff80
	v_add_u32_e32 v16, s50, v127
	v_ashrrev_i32_e32 v17, 31, v16
	v_lshlrev_b64 v[16:17], 11, v[16:17]
	s_lshl_b32 s48, s34, 7
	v_or_b32_e32 v16, v16, v64
	v_or_b32_e32 v17, v17, v65
	v_or_b32_e32 v16, s48, v16
	v_lshl_add_u64 v[16:17], v[16:17], 1, s[38:39]
	s_add_i32 m0, s57, s35
	s_nop 0
	global_load_lds_dwordx4 v[16:17], off
	v_add_u32_e32 v16, s50, v126
	v_ashrrev_i32_e32 v17, 31, v16
	v_lshlrev_b64 v[16:17], 11, v[16:17]
	v_or_b32_e32 v16, v16, v66
	v_or_b32_e32 v17, v17, v67
	v_or_b32_e32 v16, s48, v16
	v_lshl_add_u64 v[16:17], v[16:17], 1, s[38:39]
	s_add_i32 m0, s57, s54
	s_nop 0
	global_load_lds_dwordx4 v[16:17], off
	v_add_u32_e32 v16, s50, v128
	v_ashrrev_i32_e32 v17, 31, v16
	v_lshlrev_b64 v[16:17], 11, v[16:17]
	v_or_b32_e32 v16, v16, v68
	v_or_b32_e32 v17, v17, v69
	v_or_b32_e32 v16, s48, v16
	v_lshl_add_u64 v[16:17], v[16:17], 1, s[38:39]
	s_add_i32 m0, s57, s55
	s_nop 0
	global_load_lds_dwordx4 v[16:17], off
	v_add_u32_e32 v16, s50, v129
	v_ashrrev_i32_e32 v17, 31, v16
	v_lshlrev_b64 v[16:17], 11, v[16:17]
	v_or_b32_e32 v16, v16, v70
	v_or_b32_e32 v17, v17, v71
	v_or_b32_e32 v16, s48, v16
	v_lshl_add_u64 v[16:17], v[16:17], 1, s[38:39]
	s_add_i32 m0, s57, s56
	s_nop 0
	global_load_lds_dwordx4 v[16:17], off
	s_cbranch_execnz .LBB0_537
	s_branch .LBB0_536

; template <int MODE, class Dec>
; __device__ __forceinline__ void attn_phase(const Frame& F, const bf16* Q, const bf16* K, const bf16* V, int nunits, const Dec dec, const bf16* O3, const float* L2, const float* L3) {
;     ...
;     asm volatile("s_waitcnt vmcnt(0)" ::: "memory");
;     __syncthreads();
.LBB0_558:
	s_setprio 0
	s_waitcnt vmcnt(0)
	v_readlane_b32 s80, v234, 45
	v_readlane_b32 s2, v234, 57
	v_readlane_b32 s74, v234, 41
	v_readlane_b32 s78, v234, 43
	v_readlane_b32 s81, v234, 46
	v_readlane_b32 s72, v234, 4
	v_readlane_b32 s93, v234, 47
	v_readlane_b32 s92, v234, 48
	v_readlane_b32 s3, v234, 58
	s_waitcnt vmcnt(0) lgkmcnt(0)
	s_barrier
	v_readlane_b32 s75, v234, 42
	v_readlane_b32 s79, v234, 44
